# grid-barrier code shared: SEAM(1)/(5)/(6) branch into SEAM(4)'s inlined copy (return dispatch on an SGPR id), so the single wave running the barrier protocol executes it from a warm I-cache
# speedup vs baseline: 1.0086x; 1.0084x over previous
; __device__ __forceinline__ unsigned xb_ld(unsigned* p)              { return __hip_atomic_load(p, __ATOMIC_RELAXED, __HIP_MEMORY_SCOPE_AGENT); }
; __device__ __forceinline__ unsigned xb_add(unsigned* p, unsigned v) { return __hip_atomic_fetch_add(p, v, __ATOMIC_RELAXED, __HIP_MEMORY_SCOPE_AGENT); }
; #define XB_SPIN(cond, bar) do { unsigned _sp = 0; while (cond) { __builtin_amdgcn_s_sleep(1); \
;     if ((++_sp & 255u) == 0u) { if (xb_ld(&(bar)[XB_TMO])) break; if (_sp > XB_SPIN_CAP) { atomicAdd(&(bar)[XB_TMO], 1u); break; } } } } while (0)
; #define SEAM(k) do { if (IN(k) && IN((k) + 1)) xcd_barrier(bar); } while (0)
; __device__ __forceinline__ void xcd_barrier(const XcdBarrier& b) {
;     asm volatile("s_waitcnt vmcnt(0)" ::: "memory");
;     __syncthreads();
;     if (threadIdx.x == 0) {
;         unsigned* bar = b.bar;
;         __builtin_amdgcn_s_waitcnt(0);
;         unsigned nloc = b.st[0], nx = b.st[1];
;         if (nloc == 0u) { xcd_barrier_complete(bar, b.x, nloc, nx); b.st[0] = nloc; b.st[1] = nx; }
;         const unsigned old = xb_add(&bar[XB_XSUB(b.x)], 1u);
;         const unsigned gen = old / nloc;
;         if (old + 1u == (gen + 1u) * nloc) {
;             __builtin_amdgcn_fence(__ATOMIC_RELEASE, "agent");
;             asm volatile("s_waitcnt vmcnt(0)" ::: "memory");
;             const unsigned og = xb_add(&bar[XB_TOP], 1u);
;             const unsigned tg = og / nx;
;             if (og + 1u == (tg + 1u) * nx) xb_add(&bar[XB_TOPGEN], 1u);
;             else XB_SPIN(xb_ld(&bar[XB_TOPGEN]) == tg, bar);
;             __builtin_amdgcn_fence(__ATOMIC_ACQUIRE, "agent");
;             xb_add(&bar[XB_XGEN(b.x)], 1u);
;             asm volatile("s_waitcnt vmcnt(0)" ::: "memory");
;         } else {
;             XB_SPIN(xb_ld(&bar[XB_XGEN(b.x)]) == gen, bar);
;             __builtin_amdgcn_fence(__ATOMIC_ACQUIRE, "agent");
;             asm volatile("s_waitcnt vmcnt(0)" ::: "memory");
;         }
;     }
;     __syncthreads();
; }
; __global__ void __launch_bounds__(512, 2) mk_fwd(Args args) {
;     ...
;     SEAM(1);
.LBB0_150:
	s_cmp_gt_i32 s69, 2
	s_cselect_b64 s[4:5], -1, 0
	s_and_b64 s[6:7], s[12:13], s[4:5]
	s_andn2_b64 vcc, exec, s[6:7]
	s_cbranch_vccnz .LBB0_204
	s_waitcnt vmcnt(0)
	s_waitcnt vmcnt(0)
	s_barrier
	s_and_saveexec_b64 s[6:7], s[92:93]
	s_cbranch_execz .LBB0_203
	s_mov_b32 s99, 1
	s_mov_b64 s[100:101], s[8:9]
	s_branch .Lseam_shared
.Lseam1_ret:
	s_mov_b64 s[8:9], s[100:101]

; __device__ __forceinline__ unsigned xb_add(unsigned* p, unsigned v) { return __hip_atomic_fetch_add(p, v, __ATOMIC_RELAXED, __HIP_MEMORY_SCOPE_AGENT); }
; #define SEAM(k) do { if (IN(k) && IN((k) + 1)) xcd_barrier(bar); } while (0)
; __device__ __forceinline__ void xcd_barrier(const XcdBarrier& b) {
;     asm volatile("s_waitcnt vmcnt(0)" ::: "memory");
;     __syncthreads();
;     if (threadIdx.x == 0) {
;         unsigned* bar = b.bar;
;         __builtin_amdgcn_s_waitcnt(0);
;         unsigned nloc = b.st[0], nx = b.st[1];
;         if (nloc == 0u) { xcd_barrier_complete(bar, b.x, nloc, nx); b.st[0] = nloc; b.st[1] = nx; }
;         const unsigned old = xb_add(&bar[XB_XSUB(b.x)], 1u);
;         const unsigned gen = old / nloc;
;         if (old + 1u == (gen + 1u) * nloc) {
;             __builtin_amdgcn_fence(__ATOMIC_RELEASE, "agent");
;             asm volatile("s_waitcnt vmcnt(0)" ::: "memory");
; __global__ void __launch_bounds__(512, 2) mk_fwd(Args args) {
;     ...
;     SEAM(4);
.LBB0_451:
	s_cmp_gt_i32 s69, 5
	s_cselect_b64 s[4:5], -1, 0
	s_and_b64 s[6:7], s[34:35], s[4:5]
	s_andn2_b64 vcc, exec, s[6:7]
	s_cbranch_vccnz .LBB0_505
	s_waitcnt vmcnt(0)
	s_waitcnt vmcnt(0)
	s_barrier
	s_and_saveexec_b64 s[6:7], s[92:93]
	s_cbranch_execz .LBB0_504
	s_mov_b32 s99, 4
.Lseam_shared:
	s_add_i32 s1, 0, 0x27fc0
	v_mov_b32_e32 v0, s1
	s_waitcnt vmcnt(0) expcnt(0) lgkmcnt(0)
	ds_read_b32 v2, v0
	s_add_i32 s1, 0, 0x27fc4
	v_mov_b32_e32 v0, s1
	ds_read_b32 v0, v0
	s_waitcnt lgkmcnt(1)
	v_cmp_ne_u32_e32 vcc, 0, v2
	s_cbranch_vccnz .LBB0_468
	s_add_u32 s8, s66, 0x1000
	s_addc_u32 s9, s67, 0
	s_add_u32 s10, s66, 0x1100
	s_addc_u32 s11, s67, 0
	s_add_u32 s12, s66, 0x1200
	v_readlane_b32 s1, v250, 0
	s_addc_u32 s13, s67, 0
	s_mul_i32 s1, s71, s1
	s_add_u32 s14, s66, 0x1300
	s_mul_i32 s1, s1, s70
	s_addc_u32 s15, s67, 0
	s_mov_b32 s3, 1
	v_mov_b32_e32 v16, 0
	s_branch .LBB0_456

; __device__ __forceinline__ unsigned xb_ld(unsigned* p)              { return __hip_atomic_load(p, __ATOMIC_RELAXED, __HIP_MEMORY_SCOPE_AGENT); }
; __device__ __forceinline__ unsigned xb_add(unsigned* p, unsigned v) { return __hip_atomic_fetch_add(p, v, __ATOMIC_RELAXED, __HIP_MEMORY_SCOPE_AGENT); }
; #define XB_SPIN(cond, bar) do { unsigned _sp = 0; while (cond) { __builtin_amdgcn_s_sleep(1); \
;     if ((++_sp & 255u) == 0u) { if (xb_ld(&(bar)[XB_TMO])) break; if (_sp > XB_SPIN_CAP) { atomicAdd(&(bar)[XB_TMO], 1u); break; } } } } while (0)
; __device__ __forceinline__ void xcd_barrier(const XcdBarrier& b) {
;     asm volatile("s_waitcnt vmcnt(0)" ::: "memory");
;     __syncthreads();
;     if (threadIdx.x == 0) {
;         unsigned* bar = b.bar;
;         __builtin_amdgcn_s_waitcnt(0);
;         unsigned nloc = b.st[0], nx = b.st[1];
;         if (nloc == 0u) { xcd_barrier_complete(bar, b.x, nloc, nx); b.st[0] = nloc; b.st[1] = nx; }
;         const unsigned old = xb_add(&bar[XB_XSUB(b.x)], 1u);
;         const unsigned gen = old / nloc;
;         if (old + 1u == (gen + 1u) * nloc) {
;             __builtin_amdgcn_fence(__ATOMIC_RELEASE, "agent");
;             asm volatile("s_waitcnt vmcnt(0)" ::: "memory");
;             const unsigned og = xb_add(&bar[XB_TOP], 1u);
;             const unsigned tg = og / nx;
;             if (og + 1u == (tg + 1u) * nx) xb_add(&bar[XB_TOPGEN], 1u);
;             else XB_SPIN(xb_ld(&bar[XB_TOPGEN]) == tg, bar);
;             __builtin_amdgcn_fence(__ATOMIC_ACQUIRE, "agent");
;             xb_add(&bar[XB_XGEN(b.x)], 1u);
;             asm volatile("s_waitcnt vmcnt(0)" ::: "memory");
;         } else {
;             XB_SPIN(xb_ld(&bar[XB_XGEN(b.x)]) == gen, bar);
;             __builtin_amdgcn_fence(__ATOMIC_ACQUIRE, "agent");
;             asm volatile("s_waitcnt vmcnt(0)" ::: "memory");
;         }
;     }
;     __syncthreads();
; }
.Lseam_ret:
	s_cmp_eq_u32 s99, 1
	s_cbranch_scc1 .Lseam1_ret
	s_cmp_eq_u32 s99, 5
	s_cbranch_scc1 .LBB0_588
	s_cmp_eq_u32 s99, 6
	s_cbranch_scc1 .LBB0_749

; __device__ __forceinline__ unsigned xb_ld(unsigned* p)              { return __hip_atomic_load(p, __ATOMIC_RELAXED, __HIP_MEMORY_SCOPE_AGENT); }
; __device__ __forceinline__ unsigned xb_add(unsigned* p, unsigned v) { return __hip_atomic_fetch_add(p, v, __ATOMIC_RELAXED, __HIP_MEMORY_SCOPE_AGENT); }
; #define XB_SPIN(cond, bar) do { unsigned _sp = 0; while (cond) { __builtin_amdgcn_s_sleep(1); \
;     if ((++_sp & 255u) == 0u) { if (xb_ld(&(bar)[XB_TMO])) break; if (_sp > XB_SPIN_CAP) { atomicAdd(&(bar)[XB_TMO], 1u); break; } } } } while (0)
; #define SEAM(k) do { if (IN(k) && IN((k) + 1)) xcd_barrier(bar); } while (0)
; __device__ __forceinline__ void xcd_barrier(const XcdBarrier& b) {
;     asm volatile("s_waitcnt vmcnt(0)" ::: "memory");
;     __syncthreads();
;     if (threadIdx.x == 0) {
;         unsigned* bar = b.bar;
;         __builtin_amdgcn_s_waitcnt(0);
;         unsigned nloc = b.st[0], nx = b.st[1];
;         if (nloc == 0u) { xcd_barrier_complete(bar, b.x, nloc, nx); b.st[0] = nloc; b.st[1] = nx; }
;         const unsigned old = xb_add(&bar[XB_XSUB(b.x)], 1u);
;         const unsigned gen = old / nloc;
;         if (old + 1u == (gen + 1u) * nloc) {
;             __builtin_amdgcn_fence(__ATOMIC_RELEASE, "agent");
;             asm volatile("s_waitcnt vmcnt(0)" ::: "memory");
;             const unsigned og = xb_add(&bar[XB_TOP], 1u);
;             const unsigned tg = og / nx;
;             if (og + 1u == (tg + 1u) * nx) xb_add(&bar[XB_TOPGEN], 1u);
;             else XB_SPIN(xb_ld(&bar[XB_TOPGEN]) == tg, bar);
;             __builtin_amdgcn_fence(__ATOMIC_ACQUIRE, "agent");
;             xb_add(&bar[XB_XGEN(b.x)], 1u);
;             asm volatile("s_waitcnt vmcnt(0)" ::: "memory");
;         } else {
;             XB_SPIN(xb_ld(&bar[XB_XGEN(b.x)]) == gen, bar);
;             __builtin_amdgcn_fence(__ATOMIC_ACQUIRE, "agent");
;             asm volatile("s_waitcnt vmcnt(0)" ::: "memory");
;         }
;     }
;     __syncthreads();
; }
; __global__ void __launch_bounds__(512, 2) mk_fwd(Args args) {
;     ...
;     SEAM(5);
.LBB0_535:
	s_cmp_gt_i32 s69, 6
	s_cselect_b64 s[4:5], -1, 0
	s_and_b64 s[0:1], s[6:7], s[4:5]
	s_andn2_b64 vcc, exec, s[0:1]
	s_cbranch_vccnz .LBB0_589
	s_waitcnt vmcnt(0)
	s_waitcnt vmcnt(0)
	s_barrier
	s_and_saveexec_b64 s[6:7], s[92:93]
	s_cbranch_execz .LBB0_588
	s_mov_b32 s99, 5
	s_branch .Lseam_shared

; __device__ __forceinline__ unsigned xb_ld(unsigned* p)              { return __hip_atomic_load(p, __ATOMIC_RELAXED, __HIP_MEMORY_SCOPE_AGENT); }
; __device__ __forceinline__ unsigned xb_add(unsigned* p, unsigned v) { return __hip_atomic_fetch_add(p, v, __ATOMIC_RELAXED, __HIP_MEMORY_SCOPE_AGENT); }
; #define XB_SPIN(cond, bar) do { unsigned _sp = 0; while (cond) { __builtin_amdgcn_s_sleep(1); \
;     if ((++_sp & 255u) == 0u) { if (xb_ld(&(bar)[XB_TMO])) break; if (_sp > XB_SPIN_CAP) { atomicAdd(&(bar)[XB_TMO], 1u); break; } } } } while (0)
; #define SEAM(k) do { if (IN(k) && IN((k) + 1)) xcd_barrier(bar); } while (0)
; __device__ __forceinline__ void xcd_barrier(const XcdBarrier& b) {
;     asm volatile("s_waitcnt vmcnt(0)" ::: "memory");
;     __syncthreads();
;     if (threadIdx.x == 0) {
;         unsigned* bar = b.bar;
;         __builtin_amdgcn_s_waitcnt(0);
;         unsigned nloc = b.st[0], nx = b.st[1];
;         if (nloc == 0u) { xcd_barrier_complete(bar, b.x, nloc, nx); b.st[0] = nloc; b.st[1] = nx; }
;         const unsigned old = xb_add(&bar[XB_XSUB(b.x)], 1u);
;         const unsigned gen = old / nloc;
;         if (old + 1u == (gen + 1u) * nloc) {
;             __builtin_amdgcn_fence(__ATOMIC_RELEASE, "agent");
;             asm volatile("s_waitcnt vmcnt(0)" ::: "memory");
;             const unsigned og = xb_add(&bar[XB_TOP], 1u);
;             const unsigned tg = og / nx;
;             if (og + 1u == (tg + 1u) * nx) xb_add(&bar[XB_TOPGEN], 1u);
;             else XB_SPIN(xb_ld(&bar[XB_TOPGEN]) == tg, bar);
;             __builtin_amdgcn_fence(__ATOMIC_ACQUIRE, "agent");
;             xb_add(&bar[XB_XGEN(b.x)], 1u);
;             asm volatile("s_waitcnt vmcnt(0)" ::: "memory");
;         } else {
;             XB_SPIN(xb_ld(&bar[XB_XGEN(b.x)]) == gen, bar);
;             __builtin_amdgcn_fence(__ATOMIC_ACQUIRE, "agent");
;             asm volatile("s_waitcnt vmcnt(0)" ::: "memory");
;         }
;     }
;     __syncthreads();
; }
; __global__ void __launch_bounds__(512, 2) mk_fwd(Args args) {
;     ...
;     SEAM(6);
.LBB0_696:
	s_cmp_gt_i32 s69, 7
	s_cselect_b64 s[4:5], -1, 0
	s_and_b64 s[0:1], s[8:9], s[4:5]
	s_andn2_b64 vcc, exec, s[0:1]
	s_cbranch_vccnz .LBB0_750
	s_waitcnt vmcnt(0)
	s_waitcnt vmcnt(0)
	s_barrier
	s_and_saveexec_b64 s[6:7], s[92:93]
	s_cbranch_execz .LBB0_749
	s_mov_b32 s99, 6
	s_branch .Lseam_shared
